# P3 attention items: the bias-table loads of an item are issued together and waited for once (was one wait per load)
# baseline (speedup 1.0000x reference)
; DI void attn_block2(const Params& p, int bh, int cp, char* lds) {
;     ...
;     float* tab = (float*)(lds + 49152);
;     __syncthreads();
;     for (int i = tid; i < 257; i += 256) tab[i] = p.relb[h * 257 + i] * LOG2E;
.LBB0_383:
	s_andn2_b64 vcc, exec, s[2:3]
	s_cbranch_vccnz .LBB0_418
	s_and_b32 s89, s33, 1
	v_mov_b32_e32 v82, v0
	s_movk_i32 s2, 0x101
	s_or_b32 s88, s89, s82
	v_readfirstlane_b32 s4, v82
	v_cmp_gt_i32_e32 vcc, s2, v82
	s_barrier
	s_and_saveexec_b64 s[6:7], vcc
	s_cbranch_execz .LBB0_396
	s_mulk_i32 s89, 0x101
	s_mul_i32 s2, s88, 0x101
	v_add_u32_e32 v2, s2, v82
	v_lshlrev_b32_e32 v2, 2, v2
	global_load_dword v5, v2, s[76:77]
	s_and_saveexec_b64 s[28:29], s[34:35]
	global_load_dword v6, v2, s[76:77] offset:1024
	s_mov_b64 exec, s[28:29]
	v_lshl_add_u32 v4, v82, 2, s50
	s_waitcnt vmcnt(0)
	v_mul_f32_e32 v5, 0x3fb8aa3b, v5
	ds_write_b32 v4, v5
	s_and_saveexec_b64 s[28:29], s[34:35]
	v_mul_f32_e32 v6, 0x3fb8aa3b, v6
	ds_write_b32 v4, v6 offset:1024
	s_mov_b64 exec, s[28:29]

; DI void attn_block_sample(const Params& p, int s, char* lds) {
;     int tid = threadIdx.x; asm volatile("" : "+v"(tid));
;     const int lane = tid & 63, wave = __builtin_amdgcn_readfirstlane(tid >> 6);
;     char* wl = lds + wave * 18432;
;     char* sk = wl; char* sv = wl + 8192; float* tab = (float*)(wl + 16384);
;     const u16* proj = (const u16*)(p.ws + W_PROJ);
;     const int b = s >> 3, h = s & 7; const int qrow0 = NTP + b * 16;
;     for (int i = lane; i < 257; i += 64) tab[i] = p.relb[h * 257 + i] * LOG2E;
;     const int q = lane & 15, g = lane >> 4;
;     const u16* qp = proj + (size_t)(qrow0 + q) * NC + C_Q + h * 64 + 8 * g;
;     const bf16x8 qf0 = *(const bf16x8*)qp, qf1 = *(const bf16x8*)(qp + 32);
;     float m = -INFINITY, l = 0.f; f32x4 o[4];
; #pragma unroll
;     for (int dt = 0; dt < 4; ++dt) o[dt] = (f32x4){0.f, 0.f, 0.f, 0.f};
;     const int lrow = lane >> 3, lch = lane & 7;
;     float4 rk[16], rv[16];
;     ...
;     const int d0 = 8 - 2 * wave;
;     SLOAD(d0);
.LBB0_419:
	s_andn2_b64 vcc, exec, s[2:3]
	s_cbranch_vccnz .LBB0_373
	v_mov_b32_e32 v201, v0
	s_and_b32 s3, s33, 7
	v_readfirstlane_b32 s30, v201
	s_ashr_i32 s31, s30, 6
	s_mul_i32 s2, s31, 0x4800
	v_and_b32_e32 v171, 63, v201
	s_mul_i32 s4, s3, 0x101
	s_add_i32 s36, s2, 0
	s_add_i32 s2, s36, 0x4000
	v_add_lshl_u32 v158, s4, v171, 2
	v_lshl_add_u32 v4, v171, 2, s2
	v_or_b32_e32 v5, 0xffffffc0, v171
	v_lshl_add_u64 v[2:3], s[76:77], 0, v[158:159]
	global_load_dword v6, v[2:3], off
	global_load_dword v7, v[2:3], off offset:256
	global_load_dword v8, v[2:3], off offset:512
	global_load_dword v9, v[2:3], off offset:768
	v_cmp_eq_u32_e32 vcc, 0, v171
	s_and_saveexec_b64 s[6:7], vcc
	global_load_dword v10, v[2:3], off offset:1024
	s_mov_b64 exec, s[6:7]
	s_waitcnt vmcnt(0)
	v_mul_f32_e32 v6, 0x3fb8aa3b, v6
	v_mul_f32_e32 v7, 0x3fb8aa3b, v7
	v_mul_f32_e32 v8, 0x3fb8aa3b, v8
	v_mul_f32_e32 v9, 0x3fb8aa3b, v9
	ds_write_b32 v4, v6
	ds_write_b32 v4, v7 offset:256
	ds_write_b32 v4, v8 offset:512
	ds_write_b32 v4, v9 offset:768
	s_and_saveexec_b64 s[6:7], vcc
	v_mul_f32_e32 v10, 0x3fb8aa3b, v10
	ds_write_b32 v4, v10 offset:1024
	s_mov_b64 exec, s[6:7]
	s_add_i32 s6, s33, s84
	s_lshl_b32 s2, s6, 1
	s_and_b32 s2, s2, -16
	s_addk_i32 s2, 0x4000
	v_and_b32_e32 v188, 15, v201
	v_or_b32_e32 v170, s2, v188
	v_mov_b64_e32 v[2:3], s[68:69]
	v_mad_i64_i32 v[2:3], s[28:29], v170, s43, v[2:3]
	s_lshl_b32 s4, s3, 7
	v_lshl_add_u64 v[172:173], v[2:3], 0, s[4:5]
	s_ashr_i32 s7, s6, 31
	s_lshl_b32 s4, s31, 7
	s_lshl_b64 s[6:7], s[6:7], 9
	s_ashr_i32 s29, s4, 31
	s_add_u32 s28, s6, s4
	v_and_b32_e32 v158, 48, v171
	v_lshrrev_b32_e32 v191, 3, v171
	s_addc_u32 s29, s7, s29
	v_lshlrev_b32_e32 v10, 3, v201
	v_lshl_add_u64 v[2:3], v[172:173], 0, v[158:159]
	s_lshl_b64 s[28:29], s[28:29], 6
	v_lshlrev_b32_e32 v138, 6, v191
	v_and_b32_e32 v158, 56, v10
	v_or3_b32 v10, s28, v138, v158
	v_mov_b32_e32 v11, s29
	v_lshlrev_b64 v[10:11], 2, v[10:11]
	v_lshl_add_u64 v[122:123], s[60:61], 0, v[10:11]
	global_load_dwordx4 v[6:9], v[2:3], off
	s_nop 0
	global_load_dwordx4 v[2:5], v[2:3], off offset:64
	v_lshl_add_u64 v[124:125], s[62:63], 0, v[10:11]
	global_load_dwordx4 v[10:13], v[122:123], off offset:16 nt
	global_load_dwordx4 v[14:17], v[122:123], off nt
	global_load_dwordx4 v[18:21], v[124:125], off offset:16 nt
	global_load_dwordx4 v[22:25], v[124:125], off nt
	global_load_dwordx4 v[26:29], v[122:123], off offset:2064 nt
	global_load_dwordx4 v[30:33], v[122:123], off offset:2048 nt
	global_load_dwordx4 v[34:37], v[124:125], off offset:2064 nt
	global_load_dwordx4 v[38:41], v[124:125], off offset:2048 nt
	v_add_co_u32_e32 v58, vcc, s45, v122
	v_lshl_add_u64 v[46:47], v[122:123], 0, s[14:15]
	s_nop 0
	v_addc_co_u32_e32 v59, vcc, 0, v123, vcc
	v_add_co_u32_e32 v90, vcc, s42, v122
	v_lshl_add_u64 v[54:55], v[124:125], 0, s[14:15]
	s_nop 0
	v_addc_co_u32_e32 v91, vcc, 0, v123, vcc
	v_add_co_u32_e32 v66, vcc, s45, v124
	global_load_dwordx4 v[42:45], v[90:91], off offset:-4096 nt
	s_nop 0
	global_load_dwordx4 v[46:49], v[46:47], off offset:16 nt
	v_addc_co_u32_e32 v67, vcc, 0, v125, vcc
	v_add_co_u32_e32 v98, vcc, s42, v124
	v_lshl_add_u64 v[62:63], v[122:123], 0, s[16:17]
	s_nop 0
	v_addc_co_u32_e32 v99, vcc, 0, v125, vcc
	global_load_dwordx4 v[50:53], v[98:99], off offset:-4096 nt
	s_nop 0
	global_load_dwordx4 v[54:57], v[54:55], off offset:16 nt
	v_lshl_add_u64 v[70:71], v[124:125], 0, s[16:17]
	v_add_co_u32_e32 v126, vcc, s51, v122
	global_load_dwordx4 v[58:61], v[58:59], off offset:2048 nt
	s_nop 0
	global_load_dwordx4 v[62:65], v[62:63], off offset:16 nt
	s_nop 0
	global_load_dwordx4 v[66:69], v[66:67], off offset:2048 nt
	s_nop 0
	global_load_dwordx4 v[70:73], v[70:71], off offset:16 nt
	v_lshl_add_u64 v[78:79], v[122:123], 0, s[18:19]
	v_lshl_add_u64 v[86:87], v[124:125], 0, s[18:19]
	v_addc_co_u32_e32 v127, vcc, 0, v123, vcc
	global_load_dwordx4 v[74:77], v[90:91], off nt
	s_nop 0
	global_load_dwordx4 v[78:81], v[78:79], off offset:16 nt
	s_nop 0
	global_load_dwordx4 v[82:85], v[98:99], off nt
	s_nop 0
	global_load_dwordx4 v[86:89], v[86:87], off offset:16 nt
	v_lshl_add_u64 v[94:95], v[122:123], 0, s[20:21]
	v_lshl_add_u64 v[102:103], v[124:125], 0, s[20:21]
	v_lshl_add_u64 v[110:111], v[122:123], 0, s[22:23]
	v_add_co_u32_e32 v130, vcc, s51, v124
	global_load_dwordx4 v[90:93], v[90:91], off offset:2048 nt
	s_nop 0
	global_load_dwordx4 v[94:97], v[94:95], off offset:16 nt
	s_nop 0
	global_load_dwordx4 v[98:101], v[98:99], off offset:2048 nt
	s_nop 0
	global_load_dwordx4 v[102:105], v[102:103], off offset:16 nt
	v_lshl_add_u64 v[118:119], v[124:125], 0, s[22:23]
	global_load_dwordx4 v[106:109], v[126:127], off nt
	s_nop 0
	global_load_dwordx4 v[110:113], v[110:111], off offset:16 nt
	v_addc_co_u32_e32 v131, vcc, 0, v125, vcc
	global_load_dwordx4 v[114:117], v[130:131], off nt
	s_nop 0
	global_load_dwordx4 v[118:121], v[118:119], off offset:16 nt
	v_lshl_add_u64 v[128:129], v[122:123], 0, s[24:25]
	v_lshl_add_u64 v[134:135], v[124:125], 0, s[24:25]
	global_load_dwordx4 v[122:125], v[126:127], off offset:2048 nt
	s_nop 0
	global_load_dwordx4 v[126:129], v[128:129], off offset:16 nt
	s_nop 0
	global_load_dwordx4 v[130:133], v[130:131], off offset:2048 nt
	s_nop 0
	global_load_dwordx4 v[134:137], v[134:135], off offset:16 nt
	v_and_b32_e32 v189, 48, v201
	v_or_b32_e32 v197, 8, v191
	s_waitcnt lgkmcnt(0)
	s_or_b32 s28, s4, 64
	s_ashr_i32 s29, s28, 31
	s_add_u32 s6, s6, s28
	s_addc_u32 s7, s7, s29
	s_lshl_b64 s[6:7], s[6:7], 6
	v_lshrrev_b32_e32 v190, 4, v171
	v_lshrrev_b32_e32 v212, 1, v201
	v_bitop3_b32 v139, v212, v190, 7 bitop3:0x6c
	v_lshlrev_b32_e32 v139, 4, v139
	v_lshl_add_u32 v143, v188, 7, s36
	v_add_u32_e32 v199, v143, v139
	s_cmp_gt_i32 s31, 2
	s_mov_b64 s[28:29], -1
	v_subrev_u32_e32 v202, s4, v188
	v_lshlrev_b32_e32 v196, 2, v190
	s_waitcnt vmcnt(0)
; DI void attn_block_sample(const Params& p, int s, char* lds) {
;     ...
;     const int d0 = 8 - 2 * wave;
;     SLOAD(d0);
;     asm volatile("s_waitcnt lgkmcnt(0)" ::: "memory");
;     SWRITE();
;     SLOAD(d0 - 1);
	v_cvt_pk_bf16_f32 v14, v14, v15
	v_cvt_pk_bf16_f32 v15, v16, v17
	v_cvt_pk_bf16_f32 v17, v12, v13
	v_cvt_pk_bf16_f32 v12, v18, v19
	v_lshlrev_b32_e32 v19, 4, v201
	v_lshlrev_b32_e32 v18, 7, v191
	v_and_b32_e32 v19, 0x70, v19
	v_bitop3_b32 v18, v19, v18, v189 bitop3:0xde
	v_lshrrev_b32_e32 v19, 1, v197
	v_xor_b32_e32 v19, v19, v201
	v_add_u32_e32 v192, s36, v18
	v_lshlrev_b32_e32 v18, 7, v197
	v_lshlrev_b32_e32 v19, 4, v19
	v_and_or_b32 v18, v19, s71, v18
	v_add_u32_e32 v193, s36, v18
	v_or_b32_e32 v18, 24, v191
	v_lshlrev_b32_e32 v19, 7, v18
	v_lshrrev_b32_e32 v18, 1, v18
	v_xor_b32_e32 v18, v18, v201
	v_lshlrev_b32_e32 v18, 4, v18
	v_and_or_b32 v18, v18, s71, v19
	v_add_u32_e32 v194, s36, v18
	v_or_b32_e32 v18, 40, v191
	v_lshlrev_b32_e32 v19, 7, v18
	v_lshrrev_b32_e32 v18, 1, v18
	v_xor_b32_e32 v18, v18, v201
	v_cvt_pk_bf16_f32 v16, v10, v11
	v_cvt_pk_bf16_f32 v10, v22, v23
	v_cvt_pk_bf16_f32 v11, v24, v25
	v_cvt_pk_bf16_f32 v13, v20, v21
	v_lshlrev_b32_e32 v18, 4, v18
	ds_write_b128 v192, v[14:17]
	ds_write_b128 v192, v[10:13] offset:8192
	v_cvt_pk_bf16_f32 v10, v30, v31
	v_cvt_pk_bf16_f32 v11, v32, v33
	v_cvt_pk_bf16_f32 v12, v26, v27
	v_cvt_pk_bf16_f32 v13, v28, v29
	v_and_or_b32 v18, v18, s71, v19
	v_cvt_pk_bf16_f32 v14, v38, v39
	v_cvt_pk_bf16_f32 v15, v40, v41
	v_cvt_pk_bf16_f32 v16, v34, v35
	v_cvt_pk_bf16_f32 v17, v36, v37
	ds_write_b128 v193, v[10:13]
	ds_write_b128 v193, v[14:17] offset:8192
	v_cvt_pk_bf16_f32 v10, v42, v43
	v_cvt_pk_bf16_f32 v11, v44, v45
	v_cvt_pk_bf16_f32 v12, v46, v47
	v_cvt_pk_bf16_f32 v13, v48, v49
	v_add_u32_e32 v195, s36, v18
	v_or_b32_e32 v18, 56, v191
	v_cvt_pk_bf16_f32 v14, v50, v51
	v_cvt_pk_bf16_f32 v15, v52, v53
	v_cvt_pk_bf16_f32 v16, v54, v55
	v_cvt_pk_bf16_f32 v17, v56, v57
	ds_write_b128 v192, v[10:13] offset:2048
	ds_write_b128 v192, v[14:17] offset:10240
	v_cvt_pk_bf16_f32 v10, v58, v59
	v_cvt_pk_bf16_f32 v11, v60, v61
	v_cvt_pk_bf16_f32 v12, v62, v63
	v_cvt_pk_bf16_f32 v13, v64, v65
	v_lshlrev_b32_e32 v19, 7, v18
	v_lshrrev_b32_e32 v18, 1, v18
	v_cvt_pk_bf16_f32 v14, v66, v67
	v_cvt_pk_bf16_f32 v15, v68, v69
	v_cvt_pk_bf16_f32 v16, v70, v71
	v_cvt_pk_bf16_f32 v17, v72, v73
	ds_write_b128 v194, v[10:13]
	ds_write_b128 v194, v[14:17] offset:8192
	v_cvt_pk_bf16_f32 v10, v74, v75
	v_cvt_pk_bf16_f32 v11, v76, v77
	v_cvt_pk_bf16_f32 v12, v78, v79
	v_cvt_pk_bf16_f32 v13, v80, v81
	v_xor_b32_e32 v18, v18, v201
	v_cvt_pk_bf16_f32 v14, v82, v83
	v_cvt_pk_bf16_f32 v15, v84, v85
	v_cvt_pk_bf16_f32 v16, v86, v87
	v_cvt_pk_bf16_f32 v17, v88, v89
	ds_write_b128 v192, v[10:13] offset:4096
	ds_write_b128 v192, v[14:17] offset:12288
	v_cvt_pk_bf16_f32 v10, v90, v91
	v_cvt_pk_bf16_f32 v11, v92, v93
	v_cvt_pk_bf16_f32 v12, v94, v95
	v_cvt_pk_bf16_f32 v13, v96, v97
	v_lshlrev_b32_e32 v18, 4, v18
	v_cvt_pk_bf16_f32 v14, v98, v99
	v_cvt_pk_bf16_f32 v15, v100, v101
	v_cvt_pk_bf16_f32 v16, v102, v103
	v_cvt_pk_bf16_f32 v17, v104, v105
	ds_write_b128 v195, v[10:13]
	ds_write_b128 v195, v[14:17] offset:8192
	v_cvt_pk_bf16_f32 v10, v106, v107
	v_cvt_pk_bf16_f32 v11, v108, v109
	v_cvt_pk_bf16_f32 v12, v110, v111
	v_cvt_pk_bf16_f32 v13, v112, v113
	v_and_or_b32 v18, v18, s71, v19
	v_cvt_pk_bf16_f32 v14, v114, v115
	v_cvt_pk_bf16_f32 v15, v116, v117
	v_cvt_pk_bf16_f32 v16, v118, v119
	v_cvt_pk_bf16_f32 v17, v120, v121
	ds_write_b128 v192, v[10:13] offset:6144
	ds_write_b128 v192, v[14:17] offset:14336
	v_cvt_pk_bf16_f32 v10, v122, v123
	v_cvt_pk_bf16_f32 v11, v124, v125
	v_cvt_pk_bf16_f32 v12, v126, v127
	v_cvt_pk_bf16_f32 v13, v128, v129
	v_add_u32_e32 v198, s36, v18
	v_cvt_pk_bf16_f32 v14, v130, v131
	v_cvt_pk_bf16_f32 v15, v132, v133
	v_cvt_pk_bf16_f32 v16, v134, v135
	v_cvt_pk_bf16_f32 v17, v136, v137
	ds_write_b128 v198, v[10:13]
	ds_write_b128 v198, v[14:17] offset:8192
	v_or3_b32 v10, s6, v138, v158
	v_mov_b32_e32 v11, s7
	v_lshlrev_b64 v[10:11], 2, v[10:11]
	v_lshl_add_u64 v[12:13], s[60:61], 0, v[10:11]
	v_add_co_u32_e32 v18, vcc, s45, v12
	v_lshl_add_u64 v[10:11], s[62:63], 0, v[10:11]
	s_nop 0
	v_addc_co_u32_e32 v19, vcc, 0, v13, vcc
	v_add_co_u32_e32 v20, vcc, s42, v12
	v_lshl_add_u64 v[14:15], v[12:13], 0, s[14:15]
	s_nop 0
	v_addc_co_u32_e32 v21, vcc, 0, v13, vcc
	global_load_dwordx4 v[126:129], v[12:13], off offset:16 nt
	global_load_dwordx4 v[134:137], v[12:13], off nt
	global_load_dwordx4 v[122:125], v[10:11], off offset:16 nt
	global_load_dwordx4 v[130:133], v[10:11], off nt
	global_load_dwordx4 v[94:97], v[12:13], off offset:2064 nt
	global_load_dwordx4 v[110:113], v[12:13], off offset:2048 nt
	global_load_dwordx4 v[82:85], v[10:11], off offset:2064 nt
	global_load_dwordx4 v[106:109], v[10:11], off offset:2048 nt
	global_load_dwordx4 v[74:77], v[20:21], off offset:-4096 nt
	global_load_dwordx4 v[98:101], v[14:15], off offset:16 nt
	v_add_co_u32_e32 v14, vcc, s45, v10
	v_lshl_add_u64 v[16:17], v[10:11], 0, s[14:15]
	s_nop 0
	v_addc_co_u32_e32 v15, vcc, 0, v11, vcc
	v_add_co_u32_e32 v22, vcc, s42, v10
	v_lshl_add_u64 v[24:25], v[10:11], 0, s[16:17]
	s_nop 0
	v_addc_co_u32_e32 v23, vcc, 0, v11, vcc
	global_load_dwordx4 v[114:117], v[22:23], off offset:-4096 nt
	global_load_dwordx4 v[118:121], v[16:17], off offset:16 nt
	v_lshl_add_u64 v[16:17], v[12:13], 0, s[16:17]
	global_load_dwordx4 v[102:105], v[18:19], off offset:2048 nt
	global_load_dwordx4 v[90:93], v[16:17], off offset:16 nt
	global_load_dwordx4 v[86:89], v[14:15], off offset:2048 nt
	global_load_dwordx4 v[78:81], v[24:25], off offset:16 nt
	v_lshl_add_u64 v[14:15], v[12:13], 0, s[18:19]
	v_lshl_add_u64 v[16:17], v[10:11], 0, s[18:19]
	global_load_dwordx4 v[66:69], v[20:21], off nt
	global_load_dwordx4 v[62:65], v[14:15], off offset:16 nt
	global_load_dwordx4 v[58:61], v[22:23], off nt
	global_load_dwordx4 v[70:73], v[16:17], off offset:16 nt
	v_lshl_add_u64 v[14:15], v[12:13], 0, s[20:21]
	v_add_co_u32_e32 v18, vcc, s51, v12
	v_lshl_add_u64 v[16:17], v[10:11], 0, s[20:21]
	global_load_dwordx4 v[54:57], v[20:21], off offset:2048 nt
	global_load_dwordx4 v[50:53], v[14:15], off offset:16 nt
	global_load_dwordx4 v[46:49], v[22:23], off offset:2048 nt
	global_load_dwordx4 v[42:45], v[16:17], off offset:16 nt
	v_lshl_add_u64 v[14:15], v[12:13], 0, s[22:23]
	v_addc_co_u32_e32 v19, vcc, 0, v13, vcc
	global_load_dwordx4 v[34:37], v[18:19], off nt
	global_load_dwordx4 v[26:29], v[14:15], off offset:16 nt
	v_add_co_u32_e32 v14, vcc, s51, v10
	v_lshl_add_u64 v[16:17], v[10:11], 0, s[22:23]
	s_nop 0
	v_addc_co_u32_e32 v15, vcc, 0, v11, vcc
	v_lshl_add_u64 v[12:13], v[12:13], 0, s[24:25]
	v_lshl_add_u64 v[10:11], v[10:11], 0, s[24:25]
	global_load_dwordx4 v[38:41], v[14:15], off nt
	global_load_dwordx4 v[30:33], v[16:17], off offset:16 nt
	global_load_dwordx4 v[22:25], v[18:19], off offset:2048 nt
	s_nop 0
	global_load_dwordx4 v[18:21], v[12:13], off offset:16 nt
	s_nop 0
	global_load_dwordx4 v[14:17], v[14:15], off offset:2048 nt
	s_nop 0
	global_load_dwordx4 v[10:13], v[10:11], off offset:16 nt
	v_bfe_u32 v138, v201, 1, 3
	s_waitcnt lgkmcnt(0)
; DI float xmax16(float v) { const unsigned x = __float_as_uint(v); auto r = __builtin_amdgcn_permlane16_swap(x, x, false, false); return fmaxf(__uint_as_float(r[0]), __uint_as_float(r[1])); }
; DI float xmax32(float v) { const unsigned x = __float_as_uint(v); auto r = __builtin_amdgcn_permlane32_swap(x, x, false, false); return fmaxf(__uint_as_float(r[0]), __uint_as_float(r[1])); }
; DI void attn_tile(const char* sk, const char* sv, const float* tab, const bf16x8& qf0, const bf16x8& qf1, float& m, float& l, f32x4 (&o)[4], int qpos, int dlt, int nvalid, int lane) {
;     const int q = lane & 15, g = lane >> 4;
;     const float C2 = 0.125f * LOG2E;
;     f32x4 sc[4];
; #pragma unroll
;     for (int kt = 0; kt < 4; ++kt) {
;         const bf16x8 a0 = *(const bf16x8*)(sk + swz(16 * kt + q, g)); const bf16x8 a1 = *(const bf16x8*)(sk + swz(16 * kt + q, 4 + g));
;         f32x4 s = {0.f, 0.f, 0.f, 0.f};
;         s = __builtin_amdgcn_mfma_f32_16x16x32_bf16(a0, qf0, s, 0, 0, 0); s = __builtin_amdgcn_mfma_f32_16x16x32_bf16(a1, qf1, s, 0, 0, 0);
;         sc[kt] = s;
;     }
;     float mx = -INFINITY;
;     if (dlt >= 3) {
;         const float bc = tab[256];
; #pragma unroll
;         for (int kt = 0; kt < 4; ++kt)
; #pragma unroll
;             for (int e = 0; e < 4; ++e) { const float s = sc[kt][e] * C2 + bc; sc[kt][e] = s; mx = fmaxf(mx, s); }
;     } else {
; #pragma unroll
;         for (int kt = 0; kt < 4; ++kt)
; #pragma unroll
;             for (int e = 0; e < 4; ++e) { const int key = 16 * kt + 4 * g + e; int rel = qpos - key + dlt * 64; rel = rel < -128 ? -128 : (rel > 128 ? 128 : rel);
;                 float s = sc[kt][e] * C2 + tab[rel + 128]; if (key >= nvalid) s = -INFINITY; sc[kt][e] = s; mx = fmaxf(mx, s); }
;     }
;     mx = xmax16(mx); mx = xmax32(mx);
	v_bitop3_b32 v138, v190, v138, 4 bitop3:0x36
	v_lshlrev_b32_e32 v142, 4, v138
	ds_read_b128 v[138:141], v199
	v_add_u32_e32 v200, v143, v142
	ds_read_b128 v[142:145], v200
	s_waitcnt lgkmcnt(0)
	v_mfma_f32_16x16x32_bf16 v[138:141], v[138:141], v[6:9], 0
	s_cselect_b64 s[6:7], -1, 0
	s_and_b64 vcc, exec, s[6:7]
	v_mfma_f32_16x16x32_bf16 v[138:141], v[142:145], v[2:5], v[138:141]
	ds_read_b128 v[142:145], v199 offset:2048
	ds_read_b128 v[146:149], v200 offset:2048
	s_waitcnt lgkmcnt(1)
	v_mfma_f32_16x16x32_bf16 v[142:145], v[142:145], v[6:9], 0
	s_waitcnt lgkmcnt(0)
	v_mfma_f32_16x16x32_bf16 v[146:149], v[146:149], v[2:5], v[142:145]
	s_nop 5
	ds_read_b128 v[142:145], v199 offset:4096
	ds_read_b128 v[150:153], v200 offset:4096
	s_waitcnt lgkmcnt(1)
	v_mfma_f32_16x16x32_bf16 v[142:145], v[142:145], v[6:9], 0
	s_waitcnt lgkmcnt(0)
	v_mfma_f32_16x16x32_bf16 v[142:145], v[150:153], v[2:5], v[142:145]
	ds_read_b128 v[150:153], v199 offset:6144
	ds_read_b128 v[154:157], v200 offset:6144
	s_waitcnt lgkmcnt(1)
	v_mfma_f32_16x16x32_bf16 v[150:153], v[150:153], v[6:9], 0
	s_waitcnt lgkmcnt(0)
	v_mfma_f32_16x16x32_bf16 v[150:153], v[154:157], v[2:5], v[150:153]
	s_cbranch_vccz .LBB0_424
	v_lshlrev_b32_e32 v213, 2, v190
	v_add_u32_e32 v154, 0x200, v202
	v_sub_u32_e32 v155, v154, v213
	v_xad_u32 v154, v213, -1, v154
	v_med3_i32 v154, v154, s64, v187
	v_sub_u32_e32 v178, v202, v213
	v_lshl_add_u32 v156, v154, 2, s36
	v_add_u32_e32 v154, 0x1fe, v178
	v_med3_i32 v154, v154, s64, v187
	v_lshl_add_u32 v157, v154, 2, s36
	v_add_u32_e32 v154, 0x1fd, v178
	v_med3_i32 v154, v154, s64, v187
	v_lshl_add_u32 v174, v154, 2, s36
	v_add_u32_e32 v154, 0x1f0, v178
	v_med3_i32 v154, v154, s64, v187
	v_lshl_add_u32 v175, v154, 2, s36
	v_add_u32_e32 v154, 0x1ef, v178
	v_med3_i32 v154, v154, s64, v187
	v_lshl_add_u32 v176, v154, 2, s36
	v_add_u32_e32 v154, 0x1ee, v178
	v_med3_i32 v154, v154, s64, v187
	v_med3_i32 v155, v155, s64, v187
	v_lshl_add_u32 v177, v154, 2, s36
	v_add_u32_e32 v154, 0x1ed, v178
	v_lshl_add_u32 v155, v155, 2, s36
	v_med3_i32 v154, v154, s64, v187
	v_lshl_add_u32 v179, v154, 2, s36
	ds_read_b32 v154, v155 offset:16896
	ds_read_b32 v155, v156 offset:16896
	ds_read_b32 v156, v157 offset:16896
	ds_read_b32 v157, v174 offset:16896
	ds_read_b32 v174, v175 offset:16896
	ds_read_b32 v175, v176 offset:16896
	ds_read_b32 v176, v177 offset:16896
	ds_read_b32 v177, v179 offset:16896
	s_waitcnt lgkmcnt(6)
	v_pk_fma_f32 v[154:155], v[138:139], s[10:11], v[154:155] op_sel_hi:[1,0,1]
	s_waitcnt lgkmcnt(4)
	v_pk_fma_f32 v[156:157], v[140:141], s[10:11], v[156:157] op_sel_hi:[1,0,1]
	v_max3_f32 v179, v154, s65, v155
	v_max3_f32 v179, v179, v156, v157
	s_waitcnt lgkmcnt(2)
	v_pk_fma_f32 v[174:175], v[146:147], s[10:11], v[174:175] op_sel_hi:[1,0,1]
	s_waitcnt lgkmcnt(0)
	v_pk_fma_f32 v[176:177], v[148:149], s[10:11], v[176:177] op_sel_hi:[1,0,1]
	v_max3_f32 v179, v179, v174, v175
	v_max3_f32 v203, v179, v176, v177
	v_add_u32_e32 v179, 0x1e0, v178
	v_add_u32_e32 v180, 0x1df, v178
	v_add_u32_e32 v181, 0x1de, v178
	v_add_u32_e32 v182, 0x1dd, v178
	v_add_u32_e32 v183, 0x1d0, v178
	v_add_u32_e32 v184, 0x1cf, v178
	v_add_u32_e32 v185, 0x1ce, v178
	v_med3_i32 v179, v179, s64, v187
	v_med3_i32 v180, v180, s64, v187
	v_med3_i32 v181, v181, s64, v187
	v_med3_i32 v182, v182, s64, v187
	v_med3_i32 v183, v183, s64, v187
	v_med3_i32 v184, v184, s64, v187
	v_med3_i32 v185, v185, s64, v187
	v_add_u32_e32 v178, 0x1cd, v178
	v_lshl_add_u32 v179, v179, 2, s36
	v_lshl_add_u32 v180, v180, 2, s36
	v_lshl_add_u32 v181, v181, 2, s36
	v_lshl_add_u32 v182, v182, 2, s36
	v_lshl_add_u32 v183, v183, 2, s36
	v_lshl_add_u32 v184, v184, 2, s36
	v_lshl_add_u32 v185, v185, 2, s36
	v_med3_i32 v178, v178, s64, v187
	v_lshl_add_u32 v204, v178, 2, s36
	ds_read_b32 v178, v179 offset:16896
	ds_read_b32 v179, v180 offset:16896
	ds_read_b32 v180, v181 offset:16896
	ds_read_b32 v181, v182 offset:16896
	ds_read_b32 v182, v183 offset:16896
	ds_read_b32 v183, v184 offset:16896
	ds_read_b32 v184, v185 offset:16896
	ds_read_b32 v185, v204 offset:16896
	s_waitcnt lgkmcnt(6)
	v_pk_fma_f32 v[178:179], v[142:143], s[10:11], v[178:179] op_sel_hi:[1,0,1]
	s_waitcnt lgkmcnt(4)
	v_pk_fma_f32 v[180:181], v[144:145], s[10:11], v[180:181] op_sel_hi:[1,0,1]
	v_max3_f32 v203, v203, v178, v179
	v_max3_f32 v203, v203, v180, v181
	s_waitcnt lgkmcnt(2)
	v_pk_fma_f32 v[182:183], v[150:151], s[10:11], v[182:183] op_sel_hi:[1,0,1]
	s_waitcnt lgkmcnt(0)
	v_pk_fma_f32 v[184:185], v[152:153], s[10:11], v[184:185] op_sel_hi:[1,0,1]
	v_max3_f32 v203, v203, v182, v183
	v_max3_f32 v203, v203, v184, v185
	s_mov_b64 s[28:29], 0
